# plus S5 unit start: second- and third-stage constant loads requested behind the first three (one L2 round trip instead of three)
# speedup vs baseline: 1.0162x; 1.0028x over previous
.LBB0_646:
	s_or_b64 exec, exec, s[20:21]
	v_mov_b32_e32 v2, s59
	s_waitcnt lgkmcnt(0)
	s_barrier
	ds_read_b32 v2, v2
	s_movk_i32 s20, 0x7f
	s_waitcnt lgkmcnt(0)
	v_mov_b32_e32 v249, v2
	v_cmp_lt_i32_e32 vcc, s20, v2
	v_readfirstlane_b32 s26, v2
	s_mov_b64 s[20:21], -1
	s_cbranch_vccnz .LBB0_641
	s_ashr_i32 s50, s26, 1
	s_ashr_i32 s51, s50, 31
	v_readlane_b32 s4, v251, 28
	s_lshl_b64 s[20:21], s[50:51], 2
	v_readlane_b32 s16, v251, 40
	v_readlane_b32 s17, v251, 41
	s_add_u32 s20, s16, s20
	s_addc_u32 s21, s17, s21
	global_load_dword v4, v173, s[20:21]
	v_lshl_or_b32 v14, s50, 6, v170
	v_ashrrev_i32_e32 v15, 31, v14
	v_readlane_b32 s14, v251, 38
	v_readlane_b32 s15, v251, 39
	v_lshlrev_b64 v[2:3], 2, v[14:15]
	v_readlane_b32 s12, v251, 36
	v_lshl_add_u64 v[6:7], s[14:15], 0, v[2:3]
	v_readlane_b32 s13, v251, 37
	global_load_dword v23, v[6:7], off
	v_readlane_b32 s5, v251, 29
	v_lshl_add_u64 v[8:9], s[12:13], 0, v[2:3]
	global_load_dword v22, v[8:9], off
	v_lshlrev_b64 v[84:85], 6, v[14:15]
	v_lshl_add_u64 v[86:87], v[176:177], 0, v[84:85]
	v_lshl_add_u64 v[84:85], v[174:175], 0, v[84:85]
	v_or_b32_e32 v88, 32, v14
	v_ashrrev_i32_e32 v89, 31, v88
	v_lshlrev_b64 v[88:89], 6, v[88:89]
	v_lshl_add_u64 v[90:91], v[174:175], 0, v[88:89]
	v_lshl_add_u64 v[88:89], v[176:177], 0, v[88:89]
	global_load_dwordx4 v[50:53], v[84:85], off offset:16
	global_load_dwordx4 v[54:57], v[84:85], off
	global_load_dword v58, v[6:7], off offset:128
	global_load_dword v59, v[8:9], off offset:128
	global_load_dwordx4 v[60:63], v[86:87], off offset:16
	global_load_dwordx4 v[64:67], v[86:87], off
	global_load_dwordx4 v[68:71], v[88:89], off offset:16
	global_load_dwordx4 v[72:75], v[88:89], off
	global_load_dwordx4 v[76:79], v[90:91], off offset:16
	global_load_dwordx4 v[80:83], v[90:91], off
	v_readlane_b32 s6, v251, 30
	v_readlane_b32 s7, v251, 31
	v_readlane_b32 s8, v251, 32
	v_readlane_b32 s9, v251, 33
	v_readlane_b32 s10, v251, 34
	v_readlane_b32 s11, v251, 35
	v_readlane_b32 s18, v251, 42
	v_readlane_b32 s19, v251, 43
	s_waitcnt vmcnt(2)
	v_mul_f32_e32 v2, 0x3fb8aa3b, v4
	v_fma_f32 v3, v4, s60, -v2
	v_rndne_f32_e32 v5, v2
	v_fmac_f32_e32 v3, 0x32a5705f, v4
	v_sub_f32_e32 v2, v2, v5
	v_add_f32_e32 v2, v2, v3
	v_cvt_i32_f32_e32 v5, v5
	v_exp_f32_e32 v2, v2
	v_cmp_ngt_f32_e32 vcc, s61, v4
	v_ldexp_f32 v2, v2, v5
	s_nop 0
	v_cndmask_b32_e32 v2, 0, v2, vcc
	v_cmp_nlt_f32_e32 vcc, s62, v4
	s_nop 1
	v_cndmask_b32_e32 v16, v226, v2, vcc
	s_waitcnt vmcnt(1)
	v_mul_f32_e32 v26, v16, v23
	v_and_b32_e32 v27, 0x7fffffff, v26
	v_cmp_nlt_f32_e64 s[52:53], |v26|, s82
	s_and_saveexec_b64 s[20:21], s[52:53]
	s_xor_b64 s[54:55], exec, s[20:21]
	s_cbranch_execz .LBB0_649
	v_lshrrev_b32_e32 v2, 23, v27
	v_add_u32_e32 v2, 0xffffff88, v2
	v_cmp_lt_u32_e32 vcc, 63, v2
	s_nop 1
	v_cndmask_b32_e32 v3, 0, v227, vcc
	v_add_u32_e32 v2, v3, v2
	v_cmp_lt_u32_e64 s[20:21], 31, v2
	s_nop 1
	v_cndmask_b32_e64 v3, 0, v228, s[20:21]
	v_add_u32_e32 v2, v3, v2
	v_cmp_lt_u32_e64 s[22:23], 31, v2
	s_nop 1
	v_cndmask_b32_e64 v3, 0, v228, s[22:23]
	v_add_u32_e32 v17, v3, v2
	v_and_b32_e32 v2, 0x7fffff, v27
	v_or_b32_e32 v24, 0x800000, v2
	v_mad_u64_u32 v[2:3], s[24:25], v24, s83, 0
	v_mov_b32_e32 v172, v3
	v_mad_u64_u32 v[4:5], s[24:25], v24, s84, v[172:173]
	v_mov_b32_e32 v172, v5
	v_mad_u64_u32 v[10:11], s[24:25], v24, s63, v[172:173]
	v_mov_b32_e32 v172, v11
	v_mad_u64_u32 v[12:13], s[24:25], v24, s85, v[172:173]
	v_mov_b32_e32 v172, v13
	v_mad_u64_u32 v[18:19], s[24:25], v24, s68, v[172:173]
	v_mov_b32_e32 v172, v19
	v_mad_u64_u32 v[20:21], s[24:25], v24, s69, v[172:173]
	v_mov_b32_e32 v172, v21
	v_mad_u64_u32 v[24:25], s[24:25], v24, s70, v[172:173]
	v_cndmask_b32_e32 v3, v20, v12, vcc
	v_cndmask_b32_e32 v5, v24, v18, vcc
	v_cndmask_b32_e32 v13, v25, v20, vcc
	v_cndmask_b32_e64 v11, v5, v3, s[20:21]
	v_cndmask_b32_e64 v5, v13, v5, s[20:21]
	v_cndmask_b32_e32 v13, v18, v10, vcc
	v_cndmask_b32_e64 v3, v3, v13, s[20:21]
	v_cndmask_b32_e32 v4, v12, v4, vcc
	v_cndmask_b32_e64 v5, v5, v11, s[22:23]
	v_cndmask_b32_e64 v11, v11, v3, s[22:23]
	v_sub_u32_e32 v18, 32, v17
	v_cndmask_b32_e64 v12, v13, v4, s[20:21]
	v_alignbit_b32 v19, v5, v11, v18
	v_cmp_eq_u32_e64 s[24:25], 0, v17
	v_cndmask_b32_e64 v3, v3, v12, s[22:23]
	v_alignbit_b32 v13, v11, v3, v18
	v_cndmask_b32_e64 v5, v19, v5, s[24:25]
	v_cndmask_b32_e32 v2, v10, v2, vcc
	v_cndmask_b32_e64 v11, v13, v11, s[24:25]
	v_bfe_u32 v19, v5, 29, 1
	v_cndmask_b32_e64 v2, v4, v2, s[20:21]
	v_alignbit_b32 v13, v5, v11, 30
	v_sub_u32_e32 v20, 0, v19
	v_cndmask_b32_e64 v2, v12, v2, s[22:23]
	v_xor_b32_e32 v13, v13, v20
	v_alignbit_b32 v4, v3, v2, v18
	v_cndmask_b32_e64 v3, v4, v3, s[24:25]
	v_ffbh_u32_e32 v10, v13
	v_alignbit_b32 v4, v11, v3, 30
	v_min_u32_e32 v10, 32, v10
	v_alignbit_b32 v2, v3, v2, 30
	v_xor_b32_e32 v4, v4, v20
	v_sub_u32_e32 v11, 31, v10
	v_xor_b32_e32 v2, v2, v20
	v_alignbit_b32 v12, v13, v4, v11
	v_alignbit_b32 v2, v4, v2, v11
	v_alignbit_b32 v3, v12, v2, 9
	v_ffbh_u32_e32 v4, v3
	v_min_u32_e32 v4, 32, v4
	v_lshrrev_b32_e32 v17, 29, v5
	v_not_b32_e32 v11, v4
	v_alignbit_b32 v2, v3, v2, v11
	v_lshlrev_b32_e32 v3, 31, v17
	v_or_b32_e32 v11, 0x33000000, v3
	v_add_lshl_u32 v4, v4, v10, 23
	v_lshrrev_b32_e32 v2, 9, v2
	v_sub_u32_e32 v4, v11, v4
	v_or_b32_e32 v3, 0.5, v3
	v_lshlrev_b32_e32 v10, 23, v10
	v_or_b32_e32 v2, v4, v2
	v_lshrrev_b32_e32 v4, 9, v12
	v_sub_u32_e32 v3, v3, v10
	v_or_b32_e32 v3, v4, v3
	v_mul_f32_e32 v4, 0x3fc90fda, v3
	v_fma_f32 v10, v3, s71, -v4
	v_fmac_f32_e32 v10, 0x33a22168, v3
	v_fmac_f32_e32 v10, 0x3fc90fda, v2
	v_lshrrev_b32_e32 v2, 30, v5
	v_add_f32_e32 v30, v4, v10
	v_add_u32_e32 v29, v19, v2
	s_andn2_saveexec_b64 s[20:21], s[54:55]
	s_branch .LBB0_650

.LBB0_655:
	s_or_b64 exec, exec, s[20:21]
	v_lshlrev_b64 v[2:3], 6, v[14:15]
	v_lshl_add_u64 v[10:11], v[174:175], 0, v[2:3]
	v_lshl_add_u64 v[18:19], v[176:177], 0, v[2:3]
	s_waitcnt vmcnt(0)
	v_mov_b64_e32 v[2:3], v[50:51]
	v_mov_b64_e32 v[4:5], v[52:53]
	s_nop 0
	v_mov_b64_e32 v[10:11], v[54:55]
	v_mov_b64_e32 v[12:13], v[56:57]
	s_nop 0
	v_mov_b32_e32 v25, v58
	v_mov_b32_e32 v24, v59
	s_nop 0
	v_mov_b64_e32 v[6:7], v[60:61]
	v_mov_b64_e32 v[8:9], v[62:63]
	s_nop 0
	v_mov_b64_e32 v[18:19], v[64:65]
	v_mov_b64_e32 v[20:21], v[66:67]
	s_waitcnt vmcnt(3)
	v_mul_f32_e32 v15, v16, v25
	v_and_b32_e32 v28, 0x7fffffff, v15
	v_cmp_nlt_f32_e64 s[52:53], |v15|, s82
	s_and_saveexec_b64 s[20:21], s[52:53]
	s_xor_b64 s[54:55], exec, s[20:21]
	s_cbranch_execz .LBB0_657
	v_lshrrev_b32_e32 v17, 23, v28
	v_add_u32_e32 v17, 0xffffff88, v17
	v_cmp_lt_u32_e32 vcc, 63, v17
	s_nop 1
	v_cndmask_b32_e32 v31, 0, v227, vcc
	v_add_u32_e32 v17, v31, v17
	v_cmp_lt_u32_e64 s[20:21], 31, v17
	s_nop 1
	v_cndmask_b32_e64 v31, 0, v228, s[20:21]
	v_add_u32_e32 v17, v31, v17
	v_cmp_lt_u32_e64 s[22:23], 31, v17
	s_nop 1
	v_cndmask_b32_e64 v31, 0, v228, s[22:23]
	v_add_u32_e32 v17, v31, v17
	v_and_b32_e32 v31, 0x7fffff, v28
	v_or_b32_e32 v31, 0x800000, v31
	v_mad_u64_u32 v[36:37], s[24:25], v31, s83, 0
	v_mov_b32_e32 v172, v37
	v_mad_u64_u32 v[38:39], s[24:25], v31, s84, v[172:173]
	v_mov_b32_e32 v172, v39
	v_mad_u64_u32 v[40:41], s[24:25], v31, s63, v[172:173]
	v_mov_b32_e32 v172, v41
	v_mad_u64_u32 v[42:43], s[24:25], v31, s85, v[172:173]
	v_mov_b32_e32 v172, v43
	v_mad_u64_u32 v[44:45], s[24:25], v31, s68, v[172:173]
	v_mov_b32_e32 v172, v45
	v_mad_u64_u32 v[46:47], s[24:25], v31, s69, v[172:173]
	v_mov_b32_e32 v172, v47
	v_mad_u64_u32 v[48:49], s[24:25], v31, s70, v[172:173]
	v_cndmask_b32_e32 v32, v46, v42, vcc
	v_cndmask_b32_e32 v31, v48, v44, vcc
	v_cndmask_b32_e32 v37, v49, v46, vcc
	v_cndmask_b32_e64 v35, v31, v32, s[20:21]
	v_cndmask_b32_e64 v31, v37, v31, s[20:21]
	v_cndmask_b32_e32 v37, v44, v40, vcc
	v_cndmask_b32_e64 v32, v32, v37, s[20:21]
	v_cndmask_b32_e64 v31, v31, v35, s[22:23]
	v_cndmask_b32_e64 v35, v35, v32, s[22:23]
	v_sub_u32_e32 v39, 32, v17
	v_alignbit_b32 v41, v31, v35, v39
	v_cmp_eq_u32_e64 s[24:25], 0, v17
	v_cndmask_b32_e32 v36, v40, v36, vcc
	s_nop 0
	v_cndmask_b32_e64 v17, v41, v31, s[24:25]
	v_cndmask_b32_e32 v31, v42, v38, vcc
	v_cndmask_b32_e64 v37, v37, v31, s[20:21]
	v_cndmask_b32_e64 v32, v32, v37, s[22:23]
	v_alignbit_b32 v38, v35, v32, v39
	v_cndmask_b32_e64 v35, v38, v35, s[24:25]
	v_bfe_u32 v42, v17, 29, 1
	v_cndmask_b32_e64 v31, v31, v36, s[20:21]
	v_alignbit_b32 v38, v17, v35, 30
	v_sub_u32_e32 v43, 0, v42
	v_cndmask_b32_e64 v31, v37, v31, s[22:23]
	v_xor_b32_e32 v38, v38, v43
	v_alignbit_b32 v36, v32, v31, v39
	v_cndmask_b32_e64 v32, v36, v32, s[24:25]
	v_ffbh_u32_e32 v36, v38
	v_alignbit_b32 v35, v35, v32, 30
	v_min_u32_e32 v36, 32, v36
	v_alignbit_b32 v31, v32, v31, 30
	v_xor_b32_e32 v35, v35, v43
	v_sub_u32_e32 v37, 31, v36
	v_xor_b32_e32 v31, v31, v43
	v_alignbit_b32 v38, v38, v35, v37
	v_alignbit_b32 v31, v35, v31, v37
	v_alignbit_b32 v32, v38, v31, 9
	v_ffbh_u32_e32 v35, v32
	v_min_u32_e32 v35, 32, v35
	v_lshrrev_b32_e32 v41, 29, v17
	v_not_b32_e32 v37, v35
	v_alignbit_b32 v31, v32, v31, v37
	v_lshlrev_b32_e32 v32, 31, v41
	v_or_b32_e32 v37, 0x33000000, v32
	v_add_lshl_u32 v35, v35, v36, 23
	v_lshrrev_b32_e32 v31, 9, v31
	v_sub_u32_e32 v35, v37, v35
	v_or_b32_e32 v32, 0.5, v32
	v_lshlrev_b32_e32 v36, 23, v36
	v_or_b32_e32 v31, v35, v31
	v_lshrrev_b32_e32 v35, 9, v38
	v_sub_u32_e32 v32, v32, v36
	v_or_b32_e32 v32, v35, v32
	v_mul_f32_e32 v35, 0x3fc90fda, v32
	v_fma_f32 v36, v32, s71, -v35
	v_fmac_f32_e32 v36, 0x33a22168, v32
	v_fmac_f32_e32 v36, 0x3fc90fda, v31
	v_lshrrev_b32_e32 v17, 30, v17
	v_add_f32_e32 v31, v35, v36
	v_add_u32_e32 v32, v42, v17
	s_andn2_saveexec_b64 s[20:21], s[54:55]
	s_branch .LBB0_658

.LBB0_663:
	s_or_b64 exec, exec, s[20:21]
	v_mul_f32_e32 v37, v16, v22
	v_mul_f32_e32 v17, 0x3fb8aa3b, v37
	v_fma_f32 v38, v37, s60, -v17
	v_rndne_f32_e32 v39, v17
	v_fmac_f32_e32 v38, 0x32a5705f, v37
	v_sub_f32_e32 v17, v17, v39
	v_add_f32_e32 v17, v17, v38
	v_cvt_i32_f32_e32 v38, v39
	v_exp_f32_e32 v17, v17
	v_cmp_ngt_f32_e32 vcc, s61, v37
	s_and_b32 s51, s26, 1
	s_lshl_b32 s54, s51, 1
	v_ldexp_f32 v38, v17, v38
	v_cndmask_b32_e32 v38, 0, v38, vcc
	v_cmp_nlt_f32_e32 vcc, s62, v37
	v_mov_b32_e32 v17, 0
	s_lshl_b32 s22, s50, 4
	v_cndmask_b32_e32 v37, v226, v38, vcc
	v_mul_f32_e32 v38, v30, v30
	v_fmamk_f32 v39, v38, 0xb94c1982, v223
	v_fmaak_f32 v39, v38, v39, 0xbe2aaa9d
	v_mul_f32_e32 v39, v38, v39
	v_fmac_f32_e32 v30, v30, v39
	v_fmamk_f32 v39, v38, 0x37d75334, v224
	v_fmaak_f32 v39, v38, v39, 0x3d2aabf7
	v_fmaak_f32 v39, v38, v39, 0xbf000004
	v_fma_f32 v38, v38, v39, 1.0
	v_and_b32_e32 v39, 1, v29
	v_cmp_eq_u32_e32 vcc, 0, v39
	v_lshlrev_b32_e32 v29, 30, v29
	s_ashr_i32 s23, s22, 31
	v_cndmask_b32_e64 v30, -v30, v38, vcc
	v_bitop3_b32 v29, v29, v30, s33 bitop3:0x6c
	v_mul_f32_e32 v30, v34, v34
	v_fmamk_f32 v38, v30, 0xb94c1982, v223
	v_fmaak_f32 v38, v30, v38, 0xbe2aaa9d
	v_mul_f32_e32 v38, v30, v38
	v_fmac_f32_e32 v34, v34, v38
	v_fmamk_f32 v38, v30, 0x37d75334, v224
	v_fmaak_f32 v38, v30, v38, 0x3d2aabf7
	v_fmaak_f32 v38, v30, v38, 0xbf000004
	v_fma_f32 v30, v30, v38, 1.0
	v_and_b32_e32 v38, 1, v33
	v_lshlrev_b32_e32 v33, 30, v33
	v_cmp_class_f32_e64 vcc, v26, s74
	v_and_b32_e32 v33, 0x80000000, v33
	v_xor_b32_e32 v26, v27, v26
	v_xor_b32_e32 v33, v26, v33
	v_pk_mul_f32 v[26:27], v[22:23], v[22:23]
	v_cmp_eq_u32_e64 s[20:21], 0, v38
	v_add_f32_e32 v26, v26, v27
	v_cndmask_b32_e32 v29, v229, v29, vcc
	v_cndmask_b32_e64 v30, v30, v34, s[20:21]
	v_div_scale_f32 v27, s[20:21], v26, v26, 1.0
	v_rcp_f32_e32 v34, v27
	v_xor_b32_e32 v30, v33, v30
	v_cndmask_b32_e32 v30, v229, v30, vcc
	v_mul_f32_e32 v201, v37, v30
	v_fma_f32 v30, -v27, v34, 1.0
	v_fmac_f32_e32 v34, v30, v34
	v_div_scale_f32 v30, vcc, 1.0, v26, 1.0
	v_mul_f32_e32 v33, v30, v34
	v_fma_f32 v38, -v27, v33, v30
	v_fmac_f32_e32 v33, v38, v34
	v_fma_f32 v27, -v27, v33, v30
	v_fma_f32 v200, v37, v29, -1.0
	v_div_fmas_f32 v27, v27, v34, v33
	v_mov_b32_e32 v38, v201
	v_mov_b32_e32 v39, v200
	v_div_fixup_f32 v30, v27, v26, 1.0
	v_pk_mul_f32 v[26:27], v[22:23], v[200:201]
	v_pk_mul_f32 v[22:23], v[22:23], v[38:39]
	v_add_f32_e32 v26, v26, v27
	v_sub_f32_e32 v22, v22, v23
	v_mul_f32_e32 v26, v30, v26
	v_mul_f32_e32 v22, v30, v22
	s_waitcnt vmcnt(0)
	v_pk_mul_f32 v[38:39], v[18:19], v[22:23] op_sel_hi:[1,0]
	v_pk_mul_f32 v[18:19], v[18:19], v[26:27] op_sel_hi:[1,0]
	v_pk_fma_f32 v[38:39], v[10:11], v[26:27], v[38:39] op_sel_hi:[1,0,1] neg_lo:[0,0,1] neg_hi:[0,0,1]
	v_pk_fma_f32 v[10:11], v[10:11], v[22:23], v[18:19] op_sel_hi:[1,0,1]
	v_pk_mul_f32 v[18:19], v[20:21], v[22:23] op_sel_hi:[1,0]
	v_pk_mul_f32 v[20:21], v[20:21], v[26:27] op_sel_hi:[1,0]
	v_pk_fma_f32 v[18:19], v[12:13], v[26:27], v[18:19] op_sel_hi:[1,0,1] neg_lo:[0,0,1] neg_hi:[0,0,1]
	v_pk_fma_f32 v[12:13], v[12:13], v[22:23], v[20:21] op_sel_hi:[1,0,1]
	v_pk_mul_f32 v[20:21], v[6:7], v[22:23] op_sel_hi:[1,0]
	v_pk_mul_f32 v[6:7], v[6:7], v[26:27] op_sel_hi:[1,0]
	v_pk_fma_f32 v[20:21], v[2:3], v[26:27], v[20:21] op_sel_hi:[1,0,1] neg_lo:[0,0,1] neg_hi:[0,0,1]
	v_pk_fma_f32 v[2:3], v[2:3], v[22:23], v[6:7] op_sel_hi:[1,0,1]
	v_pk_mul_f32 v[6:7], v[8:9], v[22:23] op_sel_hi:[1,0]
	v_mul_f32_e32 v231, v37, v29
	v_pk_fma_f32 v[6:7], v[4:5], v[26:27], v[6:7] op_sel_hi:[1,0,1] neg_lo:[0,0,1] neg_hi:[0,0,1]
	v_bfe_u32 v37, v39, 16, 1
	v_bfe_u32 v23, v7, 16, 1
	v_bfe_u32 v27, v6, 16, 1
	v_bfe_u32 v40, v38, 16, 1
	v_add3_u32 v38, v38, v40, s75
	v_add3_u32 v37, v39, v37, s75
	v_add3_u32 v39, v6, v27, s75
	v_add3_u32 v40, v7, v23, s75
	v_pk_mul_f32 v[6:7], v[8:9], v[26:27] op_sel_hi:[1,0]
	v_bfe_u32 v33, v19, 16, 1
	v_pk_fma_f32 v[22:23], v[4:5], v[22:23], v[6:7] op_sel_hi:[1,0,1]
	v_bfe_u32 v5, v2, 16, 1
	v_bfe_u32 v4, v3, 16, 1
	v_add3_u32 v45, v2, v5, s75
	v_or_b32_e32 v2, 32, v14
	v_add3_u32 v46, v3, v4, s75
	v_ashrrev_i32_e32 v3, 31, v2
	v_bfe_u32 v34, v18, 16, 1
	v_bfe_u32 v6, v13, 16, 1
	v_bfe_u32 v7, v12, 16, 1
	v_lshlrev_b64 v[2:3], 6, v[2:3]
	v_bfe_u32 v29, v21, 16, 1
	v_bfe_u32 v30, v20, 16, 1
	v_add3_u32 v34, v18, v34, s75
	v_add3_u32 v33, v19, v33, s75
	v_bfe_u32 v8, v11, 16, 1
	v_bfe_u32 v9, v10, 16, 1
	v_add3_u32 v43, v12, v7, s75
	v_add3_u32 v44, v13, v6, s75
	v_lshl_add_u64 v[18:19], v[174:175], 0, v[2:3]
	v_lshl_add_u64 v[6:7], v[176:177], 0, v[2:3]
	v_add3_u32 v30, v20, v30, s75
	v_add3_u32 v29, v21, v29, s75
	v_add3_u32 v41, v10, v9, s75
	v_add3_u32 v42, v11, v8, s75
	v_mov_b64_e32 v[2:3], v[68:69]
	v_mov_b64_e32 v[4:5], v[70:71]
	s_nop 0
	v_mov_b64_e32 v[6:7], v[72:73]
	v_mov_b64_e32 v[8:9], v[74:75]
	s_nop 0
	v_mov_b64_e32 v[10:11], v[76:77]
	v_mov_b64_e32 v[12:13], v[78:79]
	s_nop 0
	v_mov_b64_e32 v[18:19], v[80:81]
	v_mov_b64_e32 v[20:21], v[82:83]
	v_mul_f32_e32 v14, v16, v24
	v_mul_f32_e32 v16, 0x3fb8aa3b, v14
	v_fma_f32 v47, v14, s60, -v16
	v_rndne_f32_e32 v48, v16
	v_fmac_f32_e32 v47, 0x32a5705f, v14
	v_sub_f32_e32 v16, v16, v48
	v_add_f32_e32 v16, v16, v47
	v_bfe_u32 v26, v23, 16, 1
	v_exp_f32_e32 v16, v16
	v_cvt_i32_f32_e32 v47, v48
	v_add3_u32 v49, v23, v26, s75
	v_mul_f32_e32 v23, v31, v31
	v_bfe_u32 v27, v22, 16, 1
	v_fmamk_f32 v26, v23, 0x37d75334, v224
	v_add3_u32 v48, v22, v27, s75
	v_fmaak_f32 v26, v23, v26, 0x3d2aabf7
	v_fmamk_f32 v27, v23, 0xb94c1982, v223
	v_ldexp_f32 v16, v16, v47
	v_cmp_ngt_f32_e32 vcc, s61, v14
	v_fmaak_f32 v26, v23, v26, 0xbf000004
	v_fmaak_f32 v27, v23, v27, 0xbe2aaa9d
	v_cndmask_b32_e32 v16, 0, v16, vcc
	v_cmp_nlt_f32_e32 vcc, s62, v14
	v_and_b32_e32 v22, 1, v32
	v_fma_f32 v26, v23, v26, 1.0
	v_mul_f32_e32 v23, v23, v27
	v_cndmask_b32_e32 v16, v226, v16, vcc
	v_fmac_f32_e32 v31, v31, v23
	v_cmp_eq_u32_e32 vcc, 0, v22
	v_lshlrev_b32_e32 v14, 30, v32
	s_lshl_b64 s[24:25], s[22:23], 1
	v_cndmask_b32_e64 v22, -v31, v26, vcc
	v_bitop3_b32 v14, v14, v22, s33 bitop3:0x6c
	v_cmp_class_f32_e64 vcc, v15, s74
	v_xor_b32_e32 v15, v28, v15
	v_perm_b32 v157, v40, v39, s76
	v_cndmask_b32_e32 v22, v229, v14, vcc
	v_mul_f32_e32 v14, v36, v36
	v_fmamk_f32 v23, v14, 0xb94c1982, v223
	v_fmaak_f32 v23, v14, v23, 0xbe2aaa9d
	v_mul_f32_e32 v23, v14, v23
	v_fmac_f32_e32 v36, v36, v23
	v_fmamk_f32 v23, v14, 0x37d75334, v224
	v_fmaak_f32 v23, v14, v23, 0x3d2aabf7
	v_fmaak_f32 v23, v14, v23, 0xbf000004
	v_fma_f32 v14, v14, v23, 1.0
	v_and_b32_e32 v23, 1, v35
	v_cmp_eq_u32_e64 s[20:21], 0, v23
	v_fma_f32 v197, v16, v22, -1.0
	v_mul_f32_e32 v200, v16, v22
	v_cndmask_b32_e64 v23, v14, v36, s[20:21]
	v_lshlrev_b32_e32 v14, 30, v35
	v_and_b32_e32 v14, 0x80000000, v14
	v_xor_b32_e32 v26, v15, v14
	v_pk_mul_f32 v[14:15], v[24:25], v[24:25]
	v_xor_b32_e32 v23, v26, v23
	v_add_f32_e32 v14, v14, v15
	v_div_scale_f32 v15, s[20:21], v14, v14, 1.0
	v_rcp_f32_e32 v27, v15
	v_cndmask_b32_e32 v23, v229, v23, vcc
	v_mul_f32_e32 v196, v16, v23
	v_mov_b32_e32 v22, v197
	v_fma_f32 v23, -v15, v27, 1.0
	v_fmac_f32_e32 v27, v23, v27
	v_div_scale_f32 v23, vcc, 1.0, v14, 1.0
	v_mul_f32_e32 v26, v23, v27
	v_fma_f32 v28, -v15, v26, v23
	v_fmac_f32_e32 v26, v28, v27
	v_fma_f32 v15, -v15, v26, v23
	v_div_fmas_f32 v15, v15, v27, v26
	v_mov_b32_e32 v23, v196
	v_div_fixup_f32 v26, v15, v14, 1.0
	v_pk_mul_f32 v[14:15], v[24:25], v[196:197]
	v_pk_mul_f32 v[22:23], v[24:25], v[22:23]
	v_sub_f32_e32 v14, v14, v15
	v_add_f32_e32 v15, v22, v23
	v_mul_f32_e32 v14, v26, v14
	v_mul_f32_e32 v16, v26, v15
	s_waitcnt vmcnt(3)
	v_pk_mul_f32 v[26:27], v[2:3], v[16:17] op_sel_hi:[1,0]
	v_pk_mul_f32 v[2:3], v[2:3], v[14:15] op_sel_hi:[1,0]
	s_waitcnt vmcnt(2)
	v_pk_mul_f32 v[22:23], v[6:7], v[16:17] op_sel_hi:[1,0]
	v_pk_mul_f32 v[24:25], v[8:9], v[16:17] op_sel_hi:[1,0]
	s_waitcnt vmcnt(1)
	v_pk_fma_f32 v[26:27], v[10:11], v[14:15], v[26:27] op_sel_hi:[1,0,1]
	v_pk_mul_f32 v[6:7], v[6:7], v[14:15] op_sel_hi:[1,0]
	v_pk_mul_f32 v[8:9], v[8:9], v[14:15] op_sel_hi:[1,0]
	v_pk_fma_f32 v[2:3], v[10:11], v[16:17], v[2:3] op_sel_hi:[1,0,1] neg_lo:[0,0,1] neg_hi:[0,0,1]
	v_pk_mul_f32 v[10:11], v[4:5], v[14:15] op_sel_hi:[1,0]
	s_waitcnt vmcnt(0)
	v_pk_fma_f32 v[22:23], v[18:19], v[14:15], v[22:23] op_sel_hi:[1,0,1]
	v_pk_fma_f32 v[24:25], v[20:21], v[14:15], v[24:25] op_sel_hi:[1,0,1]
	v_pk_fma_f32 v[6:7], v[18:19], v[16:17], v[6:7] op_sel_hi:[1,0,1] neg_lo:[0,0,1] neg_hi:[0,0,1]
	v_pk_fma_f32 v[8:9], v[20:21], v[16:17], v[8:9] op_sel_hi:[1,0,1] neg_lo:[0,0,1] neg_hi:[0,0,1]
	v_pk_fma_f32 v[10:11], v[12:13], v[16:17], v[10:11] op_sel_hi:[1,0,1] neg_lo:[0,0,1] neg_hi:[0,0,1]
	v_bfe_u32 v19, v3, 16, 1
	v_bfe_u32 v20, v2, 16, 1
	v_bfe_u32 v15, v11, 16, 1
	v_add3_u32 v20, v2, v20, s75
	v_add3_u32 v19, v3, v19, s75
	v_pk_mul_f32 v[2:3], v[4:5], v[16:17] op_sel_hi:[1,0]
	v_bfe_u32 v18, v10, 16, 1
	v_pk_fma_f32 v[2:3], v[12:13], v[14:15], v[2:3] op_sel_hi:[1,0,1]
	v_bfe_u32 v21, v9, 16, 1
	v_bfe_u32 v4, v3, 16, 1
	v_add3_u32 v3, v3, v4, s75
	v_or_b32_e32 v4, s54, v171
	v_bfe_u32 v5, v2, 16, 1
	v_lshl_add_u32 v172, v4, 11, v179
	v_bfe_u32 v28, v8, 16, 1
	v_bfe_u32 v31, v7, 16, 1
	v_bfe_u32 v32, v6, 16, 1
	v_add3_u32 v10, v10, v18, s75
	v_add3_u32 v11, v11, v15, s75
	v_bfe_u32 v12, v27, 16, 1
	v_bfe_u32 v13, v26, 16, 1
	v_bfe_u32 v14, v25, 16, 1
	v_bfe_u32 v15, v24, 16, 1
	v_bfe_u32 v16, v23, 16, 1
	v_bfe_u32 v18, v22, 16, 1
	v_add3_u32 v2, v2, v5, s75
	v_lshlrev_b64 v[106:107], 11, v[172:173]
	v_add3_u32 v6, v6, v32, s75
	v_add3_u32 v7, v7, v31, s75
	v_add3_u32 v8, v8, v28, s75
	v_add3_u32 v9, v9, v21, s75
	v_add3_u32 v18, v22, v18, s75
	v_add3_u32 v16, v23, v16, s75
	v_add3_u32 v15, v24, v15, s75
	v_add3_u32 v14, v25, v14, s75
	v_add3_u32 v13, v26, v13, s75
	v_add3_u32 v12, v27, v12, s75
	v_perm_b32 v153, v3, v2, s76
	v_lshl_add_u64 v[2:3], v[106:107], 0, s[24:25]
	v_perm_b32 v156, v29, v30, s76
	v_perm_b32 v155, v33, v34, s76
	v_perm_b32 v154, v37, v38, s76
	v_perm_b32 v149, v11, v10, s76
	v_perm_b32 v148, v19, v20, s76
	v_perm_b32 v147, v9, v8, s76
	v_perm_b32 v146, v7, v6, s76
	v_perm_b32 v161, v49, v48, s76
	v_perm_b32 v160, v46, v45, s76
	v_perm_b32 v159, v44, v43, s76
	v_perm_b32 v158, v42, v41, s76
	v_perm_b32 v152, v12, v13, s76
	v_perm_b32 v151, v14, v15, s76
	v_perm_b32 v150, v16, v18, s76
	v_lshl_add_u64 v[108:109], v[194:195], 0, v[2:3]
	s_mov_b64 s[20:21], 0
	v_mov_b32_e32 v33, 0
	v_mov_b32_e32 v2, 0
	v_mov_b32_e32 v3, 0
	v_add_co_u32_e32 v4, vcc, 0xbe00000, v108
	s_nop 1
	v_addc_co_u32_e32 v5, vcc, 0, v109, vcc
	global_load_dwordx4 v[130:133], v[4:5], off
	v_add_co_u32_e32 v4, vcc, 0xbe08000, v108
	s_nop 1
	v_addc_co_u32_e32 v5, vcc, 0, v109, vcc
	global_load_dwordx4 v[134:137], v[4:5], off
	v_add_co_u32_e32 v4, vcc, 0xbe10000, v108
	s_nop 1
	v_addc_co_u32_e32 v5, vcc, 0, v109, vcc
	global_load_dwordx4 v[138:141], v[4:5], off
	v_add_co_u32_e32 v4, vcc, 0xbe18000, v108
	s_nop 1
	v_addc_co_u32_e32 v5, vcc, 0, v109, vcc
	global_load_dwordx4 v[142:145], v[4:5], off
